# EpiResid next-unit residual loads hoisted above epilogue stores (out-proj + FFN-down), saddr form, single counted vmcnt
# speedup vs baseline: 1.0325x; 1.0066x over previous
; #define PG8_STAGE(bufoff, gbase, voff) do { _Pragma("unroll") for (int _i = 0; _i < 2; ++_i) \
;     __builtin_amdgcn_global_load_lds((const unsigned*)((const char*)(gbase) + (voff)[_i]), (PG8_LAS unsigned*)(lds + (bufoff) + ldsw + _i * 8192), 16, 0, 0); } while (0)
; #define PG8_LDA(dst, b, h) do { _Pragma("unroll") for (int m = 0; m < 4; ++m) _Pragma("unroll") for (int k = 0; k < 2; ++k) dst[m][k] = *(const PG8_LAS bf16x8*)(lds + PG8_SA(b, h) + aoff + m * 2048 + k * 1024); } while (0)
; #define PG8_LDB(dst, b, h) do { _Pragma("unroll") for (int n = 0; n < 2; ++n) _Pragma("unroll") for (int k = 0; k < 2; ++k) dst[n][k] = *(const PG8_LAS bf16x8*)(lds + PG8_SB(b, h) + boff + n * 2048 + k * 1024); } while (0)
; #define PG8_MMA(ai, bj, At, Bt) do { __builtin_amdgcn_s_setprio(1); _Pragma("unroll") for (int m = 0; m < 4; ++m) _Pragma("unroll") for (int n = 0; n < 2; ++n) _Pragma("unroll") for (int k = 0; k < 2; ++k) \
;     acc[ai][bj][m][n] = __builtin_amdgcn_mfma_f32_16x16x32_bf16(Bt[n][k], At[m][k], acc[ai][bj][m][n], 0, 0, 0); __builtin_amdgcn_s_setprio(0); } while (0)
; #define PG8_WAIT_V(n) asm volatile("s_waitcnt vmcnt(" #n ")" ::: "memory")
; #define PG8_WAIT_L(n) asm volatile("s_waitcnt lgkmcnt(" #n ")" ::: "memory")
; #define PG8_BAR __builtin_amdgcn_s_barrier()
; #define PG8_SCHED __builtin_amdgcn_sched_barrier(0)
; template <class Epi>
; DI void gemm_phase(const bf16_t* __restrict__ gA, const bf16_t* __restrict__ gBt, int M, int N, int K, const Epi& E, char* lds_generic) {
;     ...
;       PG8_LDB(B0, 0, 0); PG8_SCHED; PG8_LDA(At, 0, 0); PG8_STAGE(PG8_SA(1, 1), a1 + hstep, voffA);
;       PG8_WAIT_L(8); PG8_BAR; PG8_WAIT_L(0); PG8_MMA(0, 0, At, B0); PG8_BAR; PG8_SCHED;
;       PG8_LDB(B1, 0, 1); PG8_STAGE(PG8_SB(0, 0), b2, voffB);
;       PG8_BAR; PG8_WAIT_L(0); PG8_MMA(0, 1, At, B1); PG8_BAR;
;       PG8_LDA(At, 0, 1); PG8_STAGE(PG8_SA(0, 0), a2, voffA);
;       PG8_BAR; PG8_WAIT_L(0); PG8_MMA(1, 0, At, B0); PG8_BAR; PG8_SCHED;
;       PG8_STAGE(PG8_SB(0, 1), b2 + hstep, voffB);
;       PG8_WAIT_V(6); PG8_BAR; PG8_MMA(1, 1, At, B1); PG8_BAR;
.LBB0_511:
	ds_read_b128 v[140:143], v146
	ds_read_b128 v[148:151], v146 offset:1024
	ds_read_b128 v[152:155], v146 offset:2048
	ds_read_b128 v[156:159], v146 offset:3072
	s_add_u32 s0, s28, 0xfffc0080
	s_addc_u32 s1, s29, -1
	s_cmp_eq_u32 s60, 12
	s_cselect_b32 s31, s22, s1
	s_cselect_b32 s30, s23, s0
	s_cselect_b32 s1, s27, s59
	s_cselect_b32 s0, s39, s58
	s_add_i32 m0, s6, 0xc000
	ds_read_b128 v[166:169], v145
	ds_read_b128 v[170:173], v145 offset:1024
	ds_read_b128 v[174:177], v145 offset:2048
	ds_read_b128 v[178:181], v145 offset:3072
	ds_read_b128 v[182:185], v145 offset:4096
	ds_read_b128 v[186:189], v145 offset:5120
	ds_read_b128 v[190:193], v145 offset:6144
	ds_read_b128 v[194:197], v145 offset:7168
	global_load_lds_dwordx4 v136, s[28:29]
	s_add_i32 m0, s6, 0xe000
	s_nop 0
	global_load_lds_dwordx4 v138, s[28:29]
	s_barrier
	s_waitcnt lgkmcnt(0)
	s_waitcnt lgkmcnt(0)
	v_mfma_f32_16x16x32_bf16 v[118:121], v[140:143], v[166:169], v[118:121]
	v_mfma_f32_16x16x32_bf16 v[110:113], v[152:155], v[166:169], v[110:113]
	v_mfma_f32_16x16x32_bf16 v[90:93], v[140:143], v[174:177], v[90:93]
	v_mfma_f32_16x16x32_bf16 v[82:85], v[152:155], v[174:177], v[82:85]
	v_mfma_f32_16x16x32_bf16 v[62:65], v[140:143], v[182:185], v[62:65]
	v_mfma_f32_16x16x32_bf16 v[50:53], v[152:155], v[182:185], v[50:53]
	v_mfma_f32_16x16x32_bf16 v[42:45], v[140:143], v[190:193], v[42:45]
	v_mfma_f32_16x16x32_bf16 v[22:25], v[152:155], v[190:193], v[22:25]
	v_mfma_f32_16x16x32_bf16 v[118:121], v[148:151], v[170:173], v[118:121]
	v_mfma_f32_16x16x32_bf16 v[110:113], v[156:159], v[170:173], v[110:113]
	v_mfma_f32_16x16x32_bf16 v[90:93], v[148:151], v[178:181], v[90:93]
	v_mfma_f32_16x16x32_bf16 v[82:85], v[156:159], v[178:181], v[82:85]
	v_mfma_f32_16x16x32_bf16 v[62:65], v[148:151], v[186:189], v[62:65]
	v_mfma_f32_16x16x32_bf16 v[50:53], v[156:159], v[186:189], v[50:53]
	v_mfma_f32_16x16x32_bf16 v[42:45], v[148:151], v[194:197], v[42:45]
	v_mfma_f32_16x16x32_bf16 v[22:25], v[156:159], v[194:197], v[22:25]
	s_barrier
	ds_read_b128 v[198:201], v146 offset:16384
	ds_read_b128 v[202:205], v146 offset:17408
	s_mov_b32 m0, s7
	ds_read_b128 v[206:209], v146 offset:18432
	ds_read_b128 v[210:213], v146 offset:19456
	global_load_lds_dwordx4 v0, s[0:1]
	s_mov_b32 m0, s12
	s_nop 0
	global_load_lds_dwordx4 v130, s[0:1]
	s_barrier
	s_waitcnt lgkmcnt(0)
	s_waitcnt lgkmcnt(0)
	v_mfma_f32_16x16x32_bf16 v[122:125], v[198:201], v[166:169], v[122:125]
	v_mfma_f32_16x16x32_bf16 v[126:129], v[206:209], v[166:169], v[126:129]
	v_mfma_f32_16x16x32_bf16 v[102:105], v[198:201], v[174:177], v[102:105]
	v_mfma_f32_16x16x32_bf16 v[114:117], v[206:209], v[174:177], v[114:117]
	v_mfma_f32_16x16x32_bf16 v[86:89], v[198:201], v[182:185], v[86:89]
	v_mfma_f32_16x16x32_bf16 v[98:101], v[206:209], v[182:185], v[98:101]
	v_mfma_f32_16x16x32_bf16 v[58:61], v[198:201], v[190:193], v[58:61]
	v_mfma_f32_16x16x32_bf16 v[74:77], v[206:209], v[190:193], v[74:77]
	v_mfma_f32_16x16x32_bf16 v[122:125], v[202:205], v[170:173], v[122:125]
	v_mfma_f32_16x16x32_bf16 v[126:129], v[210:213], v[170:173], v[126:129]
	v_mfma_f32_16x16x32_bf16 v[102:105], v[202:205], v[178:181], v[102:105]
	v_mfma_f32_16x16x32_bf16 v[114:117], v[210:213], v[178:181], v[114:117]
	v_mfma_f32_16x16x32_bf16 v[86:89], v[202:205], v[186:189], v[86:89]
	v_mfma_f32_16x16x32_bf16 v[98:101], v[210:213], v[186:189], v[98:101]
	v_mfma_f32_16x16x32_bf16 v[58:61], v[202:205], v[194:197], v[58:61]
	v_mfma_f32_16x16x32_bf16 v[74:77], v[210:213], v[194:197], v[74:77]
	s_mov_b32 m0, s6
	s_barrier
	ds_read_b128 v[166:169], v145 offset:16384
	ds_read_b128 v[170:173], v145 offset:17408
	ds_read_b128 v[174:177], v145 offset:18432
	ds_read_b128 v[178:181], v145 offset:19456
	ds_read_b128 v[182:185], v145 offset:20480
	ds_read_b128 v[186:189], v145 offset:21504
	ds_read_b128 v[190:193], v145 offset:22528
	ds_read_b128 v[194:197], v145 offset:23552
	global_load_lds_dwordx4 v134, s[30:31]
	s_mov_b32 m0, s13
	s_nop 0
	global_load_lds_dwordx4 v132, s[30:31]
	s_barrier
	s_waitcnt lgkmcnt(0)
	s_waitcnt lgkmcnt(0)
	v_mfma_f32_16x16x32_bf16 v[38:41], v[140:143], v[166:169], v[38:41]
	v_mfma_f32_16x16x32_bf16 v[18:21], v[152:155], v[166:169], v[18:21]
	v_mfma_f32_16x16x32_bf16 v[10:13], v[140:143], v[174:177], v[10:13]
	v_mfma_f32_16x16x32_bf16 v[2:5], v[152:155], v[174:177], v[2:5]
	v_mfma_f32_16x16x32_bf16 v[46:49], v[140:143], v[182:185], v[46:49]
	v_mfma_f32_16x16x32_bf16 v[30:33], v[152:155], v[182:185], v[30:33]
	v_mfma_f32_16x16x32_bf16 v[14:17], v[140:143], v[190:193], v[14:17]
	v_mfma_f32_16x16x32_bf16 v[6:9], v[152:155], v[190:193], v[6:9]
	v_mfma_f32_16x16x32_bf16 v[38:41], v[148:151], v[170:173], v[38:41]
	v_mfma_f32_16x16x32_bf16 v[18:21], v[156:159], v[170:173], v[18:21]
	v_mfma_f32_16x16x32_bf16 v[10:13], v[148:151], v[178:181], v[10:13]
	v_mfma_f32_16x16x32_bf16 v[2:5], v[156:159], v[178:181], v[2:5]
	v_mfma_f32_16x16x32_bf16 v[46:49], v[148:151], v[186:189], v[46:49]
	v_mfma_f32_16x16x32_bf16 v[30:33], v[156:159], v[186:189], v[30:33]
	v_mfma_f32_16x16x32_bf16 v[14:17], v[148:151], v[194:197], v[14:17]
	v_mfma_f32_16x16x32_bf16 v[6:9], v[156:159], v[194:197], v[6:9]
	s_barrier
	s_add_u32 s80, s0, 0x40000
	s_addc_u32 s81, s1, 0
	s_mov_b32 m0, s14
	s_nop 0
	global_load_lds_dwordx4 v0, s[80:81]
	s_mov_b32 m0, s15
	s_nop 0
	global_load_lds_dwordx4 v130, s[80:81]
	s_waitcnt vmcnt(6)
	s_barrier
; #define PG8_STAGE(bufoff, gbase, voff) do { _Pragma("unroll") for (int _i = 0; _i < 2; ++_i) \
;     __builtin_amdgcn_global_load_lds((const unsigned*)((const char*)(gbase) + (voff)[_i]), (PG8_LAS unsigned*)(lds + (bufoff) + ldsw + _i * 8192), 16, 0, 0); } while (0)
; #define PG8_LDA(dst, b, h) do { _Pragma("unroll") for (int m = 0; m < 4; ++m) _Pragma("unroll") for (int k = 0; k < 2; ++k) dst[m][k] = *(const PG8_LAS bf16x8*)(lds + PG8_SA(b, h) + aoff + m * 2048 + k * 1024); } while (0)
; #define PG8_LDB(dst, b, h) do { _Pragma("unroll") for (int n = 0; n < 2; ++n) _Pragma("unroll") for (int k = 0; k < 2; ++k) dst[n][k] = *(const PG8_LAS bf16x8*)(lds + PG8_SB(b, h) + boff + n * 2048 + k * 1024); } while (0)
; #define PG8_MMA(ai, bj, At, Bt) do { __builtin_amdgcn_s_setprio(1); _Pragma("unroll") for (int m = 0; m < 4; ++m) _Pragma("unroll") for (int n = 0; n < 2; ++n) _Pragma("unroll") for (int k = 0; k < 2; ++k) \
;     acc[ai][bj][m][n] = __builtin_amdgcn_mfma_f32_16x16x32_bf16(Bt[n][k], At[m][k], acc[ai][bj][m][n], 0, 0, 0); __builtin_amdgcn_s_setprio(0); } while (0)
; #define PG8_WAIT_V(n) asm volatile("s_waitcnt vmcnt(" #n ")" ::: "memory")
; #define PG8_WAIT_L(n) asm volatile("s_waitcnt lgkmcnt(" #n ")" ::: "memory")
; #define PG8_BAR __builtin_amdgcn_s_barrier()
; #define PG8_SCHED __builtin_amdgcn_sched_barrier(0)
; template <class Epi>
; DI void gemm_phase(const bf16_t* __restrict__ gA, const bf16_t* __restrict__ gBt, int M, int N, int K, const Epi& E, char* lds_generic) {
;     ...
;       PG8_LDB(B0, 1, 0); PG8_SCHED; PG8_LDA(At, 1, 0); PG8_STAGE(PG8_SA(0, 1), a2 + hstep, voffA);
;       PG8_WAIT_L(8); PG8_BAR; PG8_WAIT_L(0); PG8_MMA(0, 0, At, B0); PG8_BAR; PG8_SCHED;
;       PG8_LDB(B1, 1, 1); PG8_STAGE(PG8_SB(1, 0), b3, voffB);
;       PG8_BAR; PG8_WAIT_L(0); PG8_MMA(0, 1, At, B1); PG8_BAR;
;       PG8_LDA(At, 1, 1); PG8_STAGE(PG8_SA(1, 0), a3, voffA);
;       PG8_BAR; PG8_WAIT_L(0); PG8_MMA(1, 0, At, B0); PG8_BAR; PG8_SCHED;
;       PG8_STAGE(PG8_SB(1, 1), b3 + hstep, voffB);
;       PG8_WAIT_V(6); PG8_BAR; PG8_MMA(1, 1, At, B1); PG8_BAR;
	v_mfma_f32_16x16x32_bf16 v[54:57], v[198:201], v[166:169], v[54:57]
	v_mfma_f32_16x16x32_bf16 v[66:69], v[206:209], v[166:169], v[66:69]
	v_mfma_f32_16x16x32_bf16 v[94:97], v[198:201], v[174:177], v[94:97]
	v_mfma_f32_16x16x32_bf16 v[106:109], v[206:209], v[174:177], v[106:109]
	v_mfma_f32_16x16x32_bf16 v[70:73], v[198:201], v[182:185], v[70:73]
	v_mfma_f32_16x16x32_bf16 v[78:81], v[206:209], v[182:185], v[78:81]
	v_mfma_f32_16x16x32_bf16 v[26:29], v[198:201], v[190:193], v[26:29]
	v_mfma_f32_16x16x32_bf16 v[34:37], v[206:209], v[190:193], v[34:37]
	v_mfma_f32_16x16x32_bf16 v[54:57], v[202:205], v[170:173], v[54:57]
	v_mfma_f32_16x16x32_bf16 v[66:69], v[210:213], v[170:173], v[66:69]
	v_mfma_f32_16x16x32_bf16 v[94:97], v[202:205], v[178:181], v[94:97]
	v_mfma_f32_16x16x32_bf16 v[106:109], v[210:213], v[178:181], v[106:109]
	v_mfma_f32_16x16x32_bf16 v[70:73], v[202:205], v[186:189], v[70:73]
	v_mfma_f32_16x16x32_bf16 v[78:81], v[210:213], v[186:189], v[78:81]
	v_mfma_f32_16x16x32_bf16 v[26:29], v[202:205], v[194:197], v[26:29]
	v_mfma_f32_16x16x32_bf16 v[34:37], v[210:213], v[194:197], v[34:37]
	s_barrier
	ds_read_b128 v[140:143], v146 offset:32768
	ds_read_b128 v[148:151], v146 offset:33792
	ds_read_b128 v[152:155], v146 offset:34816
	ds_read_b128 v[156:159], v146 offset:35840
	s_add_u32 s30, s30, 0x40000
	s_addc_u32 s31, s31, 0
	s_mov_b32 m0, s16
	ds_read_b128 v[166:169], v145 offset:32768
	ds_read_b128 v[170:173], v145 offset:33792
	ds_read_b128 v[174:177], v145 offset:34816
	ds_read_b128 v[178:181], v145 offset:35840
	ds_read_b128 v[182:185], v145 offset:36864
	ds_read_b128 v[186:189], v145 offset:37888
	ds_read_b128 v[190:193], v145 offset:38912
	ds_read_b128 v[194:197], v145 offset:39936
	global_load_lds_dwordx4 v134, s[30:31]
	s_mov_b32 m0, s18
	s_nop 0
	global_load_lds_dwordx4 v132, s[30:31]
	s_barrier
	s_waitcnt lgkmcnt(0)
	s_waitcnt lgkmcnt(0)
	v_mfma_f32_16x16x32_bf16 v[118:121], v[140:143], v[166:169], v[118:121]
	v_mfma_f32_16x16x32_bf16 v[110:113], v[152:155], v[166:169], v[110:113]
	v_mfma_f32_16x16x32_bf16 v[90:93], v[140:143], v[174:177], v[90:93]
	v_mfma_f32_16x16x32_bf16 v[82:85], v[152:155], v[174:177], v[82:85]
	v_mfma_f32_16x16x32_bf16 v[62:65], v[140:143], v[182:185], v[62:65]
	v_mfma_f32_16x16x32_bf16 v[50:53], v[152:155], v[182:185], v[50:53]
	v_mfma_f32_16x16x32_bf16 v[42:45], v[140:143], v[190:193], v[42:45]
	v_mfma_f32_16x16x32_bf16 v[22:25], v[152:155], v[190:193], v[22:25]
	v_mfma_f32_16x16x32_bf16 v[118:121], v[148:151], v[170:173], v[118:121]
	v_mfma_f32_16x16x32_bf16 v[110:113], v[156:159], v[170:173], v[110:113]
	v_mfma_f32_16x16x32_bf16 v[90:93], v[148:151], v[178:181], v[90:93]
	v_mfma_f32_16x16x32_bf16 v[82:85], v[156:159], v[178:181], v[82:85]
	v_mfma_f32_16x16x32_bf16 v[62:65], v[148:151], v[186:189], v[62:65]
	v_mfma_f32_16x16x32_bf16 v[50:53], v[156:159], v[186:189], v[50:53]
	v_mfma_f32_16x16x32_bf16 v[42:45], v[148:151], v[194:197], v[42:45]
	v_mfma_f32_16x16x32_bf16 v[22:25], v[156:159], v[194:197], v[22:25]
	s_barrier
	s_mov_b32 m0, s8
	ds_read_b128 v[198:201], v146 offset:49152
	ds_read_b128 v[202:205], v146 offset:50176
	ds_read_b128 v[206:209], v146 offset:51200
	ds_read_b128 v[210:213], v146 offset:52224
	s_add_u32 s80, s0, 0x80
	s_addc_u32 s81, s1, 0
	global_load_lds_dwordx4 v0, s[80:81]
	s_mov_b32 m0, s9
	s_nop 0
	s_add_u32 s80, s0, 0x80
	s_addc_u32 s81, s1, 0
	global_load_lds_dwordx4 v130, s[80:81]
	s_barrier
	s_waitcnt lgkmcnt(0)
	s_waitcnt lgkmcnt(0)
	v_mfma_f32_16x16x32_bf16 v[122:125], v[198:201], v[166:169], v[122:125]
	v_mfma_f32_16x16x32_bf16 v[126:129], v[206:209], v[166:169], v[126:129]
	v_mfma_f32_16x16x32_bf16 v[102:105], v[198:201], v[174:177], v[102:105]
	v_mfma_f32_16x16x32_bf16 v[114:117], v[206:209], v[174:177], v[114:117]
	v_mfma_f32_16x16x32_bf16 v[86:89], v[198:201], v[182:185], v[86:89]
	v_mfma_f32_16x16x32_bf16 v[98:101], v[206:209], v[182:185], v[98:101]
	v_mfma_f32_16x16x32_bf16 v[58:61], v[198:201], v[190:193], v[58:61]
	v_mfma_f32_16x16x32_bf16 v[74:77], v[206:209], v[190:193], v[74:77]
	v_mfma_f32_16x16x32_bf16 v[122:125], v[202:205], v[170:173], v[122:125]
	v_mfma_f32_16x16x32_bf16 v[126:129], v[210:213], v[170:173], v[126:129]
	v_mfma_f32_16x16x32_bf16 v[102:105], v[202:205], v[178:181], v[102:105]
	v_mfma_f32_16x16x32_bf16 v[114:117], v[210:213], v[178:181], v[114:117]
	v_mfma_f32_16x16x32_bf16 v[86:89], v[202:205], v[186:189], v[86:89]
	v_mfma_f32_16x16x32_bf16 v[98:101], v[210:213], v[186:189], v[98:101]
	v_mfma_f32_16x16x32_bf16 v[58:61], v[202:205], v[194:197], v[58:61]
	v_mfma_f32_16x16x32_bf16 v[74:77], v[210:213], v[194:197], v[74:77]
	s_mov_b32 m0, s19
	s_barrier
	ds_read_b128 v[166:169], v145 offset:49152
	ds_read_b128 v[170:173], v145 offset:50176
	ds_read_b128 v[174:177], v145 offset:51200
	ds_read_b128 v[178:181], v145 offset:52224
	ds_read_b128 v[182:185], v145 offset:53248
	ds_read_b128 v[186:189], v145 offset:54272
	ds_read_b128 v[190:193], v145 offset:55296
	ds_read_b128 v[194:197], v145 offset:56320
	s_add_u32 s80, s30, 0xfffc0080
	s_addc_u32 s81, s31, -1
	global_load_lds_dwordx4 v134, s[80:81]
	s_mov_b32 m0, s33
	s_nop 0
	s_add_u32 s80, s30, 0xfffc0080
	s_addc_u32 s81, s31, -1
	global_load_lds_dwordx4 v132, s[80:81]
	s_barrier
; DI bf16_t f2bf(float x) { unsigned u = __float_as_uint(x); u += 0x7fffu + ((u >> 16) & 1u); return (bf16_t)(u >> 16); }
; DI float bflo(unsigned u) { return __uint_as_float(u << 16); }
; DI float bfhi(unsigned u) { return __uint_as_float(u & 0xffff0000u); }
; DI unsigned pack2(float lo, float hi) { f32x2_t v = {lo, hi}; return __builtin_bit_cast(unsigned, __builtin_convertvector(v, bf16x2_t)); }
; #define PG8_LAS __attribute__((address_space(3)))
;   DI void init(f32x4 (&acc)[2][2][4][2], const Unit& u, int wr, int wc, int fr, int fq) const {
;     ...
;       for (int m = 0; m < 4; ++m) { const bf16_t* rowp = src + (size_t)(row0 + ai * HALF + m * 16) * DM + col0;
; #pragma unroll
;         for (int bj = 0; bj < 2; ++bj) { const u32x4 w = *(const u32x4*)(rowp + bj * HALF);
;           acc[ai][bj][m][0] = (f32x4){bflo(w.x), bfhi(w.x), bflo(w.y), bfhi(w.y)} * ic; acc[ai][bj][m][1] = (f32x4){bflo(w.z), bfhi(w.z), bflo(w.w), bfhi(w.w)} * ic; } }
;   }
;   DI void operator()(const f32x4 (&acc)[2][2][4][2], const Unit& u, int wr, int wc, int fr, int fq, const PG8_LAS float*) const {
;     const int row0 = u.pm * BM + wr * 64 + fr, col0 = u.pn * BM + wc * 32 + 8 * fq;
; #pragma unroll
;     for (int ai = 0; ai < 2; ++ai)
; #pragma unroll
;       for (int m = 0; m < 4; ++m) { const int row = row0 + ai * HALF + m * 16; bf16_t* rowp = dst + (size_t)row * DM + col0; float ss = 0.f;
; #pragma unroll
;         for (int bj = 0; bj < 2; ++bj) { const f32x4 v0 = acc[ai][bj][m][0] * coef, v1 = acc[ai][bj][m][1] * coef;
;           ss += v0[0] * v0[0] + v0[1] * v0[1] + v0[2] * v0[2] + v0[3] * v0[3] + v1[0] * v1[0] + v1[1] * v1[1] + v1[2] * v1[2] + v1[3] * v1[3];
;           u32x4 w; w.x = pack2(v0[0], v0[1]); w.y = pack2(v0[2], v0[3]); w.z = pack2(v1[0], v1[1]); w.w = pack2(v1[2], v1[3]);
;           *(u32x4*)(rowp + bj * HALF) = w; }
;         ss += __shfl_xor(ss, 16); ss += __shfl_xor(ss, 32);
;         if (fq == 0) ssq[(size_t)row * 16 + u.pn * 4 + wc] = f2bf(ss); }
	s_waitcnt lgkmcnt(0)
	s_waitcnt lgkmcnt(0)
	v_mfma_f32_16x16x32_bf16 v[38:41], v[140:143], v[166:169], v[38:41]
	v_mfma_f32_16x16x32_bf16 v[18:21], v[152:155], v[166:169], v[18:21]
	v_mfma_f32_16x16x32_bf16 v[10:13], v[140:143], v[174:177], v[10:13]
	v_mfma_f32_16x16x32_bf16 v[2:5], v[152:155], v[174:177], v[2:5]
	v_mfma_f32_16x16x32_bf16 v[46:49], v[140:143], v[182:185], v[46:49]
	v_mfma_f32_16x16x32_bf16 v[30:33], v[152:155], v[182:185], v[30:33]
	v_mfma_f32_16x16x32_bf16 v[14:17], v[140:143], v[190:193], v[14:17]
	v_mfma_f32_16x16x32_bf16 v[6:9], v[152:155], v[190:193], v[6:9]
	v_mfma_f32_16x16x32_bf16 v[38:41], v[148:151], v[170:173], v[38:41]
	v_mfma_f32_16x16x32_bf16 v[18:21], v[156:159], v[170:173], v[18:21]
	v_mfma_f32_16x16x32_bf16 v[10:13], v[148:151], v[178:181], v[10:13]
	v_mfma_f32_16x16x32_bf16 v[2:5], v[156:159], v[178:181], v[2:5]
	v_mfma_f32_16x16x32_bf16 v[46:49], v[148:151], v[186:189], v[46:49]
	v_mfma_f32_16x16x32_bf16 v[30:33], v[156:159], v[186:189], v[30:33]
	v_mfma_f32_16x16x32_bf16 v[14:17], v[148:151], v[194:197], v[14:17]
	v_mfma_f32_16x16x32_bf16 v[6:9], v[156:159], v[194:197], v[6:9]
	s_barrier
	s_add_u32 s0, s0, 0x40080
	s_addc_u32 s1, s1, 0
	s_mov_b32 m0, s35
	s_nop 0
	global_load_lds_dwordx4 v0, s[0:1]
	s_mov_b32 m0, s42
	s_nop 0
	global_load_lds_dwordx4 v130, s[0:1]
	s_waitcnt vmcnt(6)
	s_barrier
	v_mfma_f32_16x16x32_bf16 v[54:57], v[198:201], v[166:169], v[54:57]
	v_mfma_f32_16x16x32_bf16 v[66:69], v[206:209], v[166:169], v[66:69]
	v_mfma_f32_16x16x32_bf16 v[94:97], v[198:201], v[174:177], v[94:97]
	v_mfma_f32_16x16x32_bf16 v[106:109], v[206:209], v[174:177], v[106:109]
	v_mfma_f32_16x16x32_bf16 v[70:73], v[198:201], v[182:185], v[70:73]
	v_mfma_f32_16x16x32_bf16 v[78:81], v[206:209], v[182:185], v[78:81]
	v_mfma_f32_16x16x32_bf16 v[26:29], v[198:201], v[190:193], v[26:29]
	v_mfma_f32_16x16x32_bf16 v[34:37], v[206:209], v[190:193], v[34:37]
	v_mfma_f32_16x16x32_bf16 v[54:57], v[202:205], v[170:173], v[54:57]
	v_mfma_f32_16x16x32_bf16 v[66:69], v[210:213], v[170:173], v[66:69]
	v_mfma_f32_16x16x32_bf16 v[94:97], v[202:205], v[178:181], v[94:97]
	v_mfma_f32_16x16x32_bf16 v[106:109], v[210:213], v[178:181], v[106:109]
	v_mfma_f32_16x16x32_bf16 v[70:73], v[202:205], v[186:189], v[70:73]
	v_mfma_f32_16x16x32_bf16 v[78:81], v[210:213], v[186:189], v[78:81]
	v_mfma_f32_16x16x32_bf16 v[26:29], v[202:205], v[194:197], v[26:29]
	v_mfma_f32_16x16x32_bf16 v[34:37], v[210:213], v[194:197], v[34:37]
	s_add_i32 s60, s60, 2
	s_add_u32 s28, s28, 0x100
	s_addc_u32 s29, s29, 0
	s_add_u32 s58, s58, 0x100
	s_addc_u32 s59, s59, 0
	s_cmp_gt_u32 s60, 13
	s_barrier
	s_cbranch_scc0 .LBB0_511
	s_cmp_eq_u64 vcc, 0
	s_cbranch_scc1 .Leinit511_skip
	v_lshl_add_u32 v246, s38, 8, v144
	v_lshl_or_b32 v247, s26, 8, v147
	v_lshlrev_b32_e32 v246, 11, v246
	v_lshl_add_u32 v246, v247, 1, v246
	global_load_dwordx4 v[166:169], v246, s[92:93]
	global_load_dwordx4 v[170:173], v246, s[92:93] offset:256
	s_add_u32 s80, s92, 0x8000
	s_addc_u32 s81, s93, 0
	global_load_dwordx4 v[174:177], v246, s[80:81]
	global_load_dwordx4 v[178:181], v246, s[80:81] offset:256
	s_add_u32 s80, s92, 0x10000
	s_addc_u32 s81, s93, 0
	global_load_dwordx4 v[182:185], v246, s[80:81]
	global_load_dwordx4 v[186:189], v246, s[80:81] offset:256
	s_add_u32 s80, s92, 0x18000
	s_addc_u32 s81, s93, 0
	global_load_dwordx4 v[190:193], v246, s[80:81]
	global_load_dwordx4 v[198:201], v246, s[80:81] offset:256
	s_add_u32 s80, s92, 0x40000
	s_addc_u32 s81, s93, 0
	global_load_dwordx4 v[194:197], v246, s[80:81]
	global_load_dwordx4 v[202:205], v246, s[80:81] offset:256
	s_add_u32 s80, s92, 0x48000
	s_addc_u32 s81, s93, 0
	global_load_dwordx4 v[206:209], v246, s[80:81]
	global_load_dwordx4 v[210:213], v246, s[80:81] offset:256
	s_add_u32 s80, s92, 0x50000
	s_addc_u32 s81, s93, 0
	global_load_dwordx4 v[214:217], v246, s[80:81]
	global_load_dwordx4 v[218:221], v246, s[80:81] offset:256
	s_add_u32 s80, s92, 0x58000
	s_addc_u32 s81, s93, 0
	global_load_dwordx4 v[238:241], v246, s[80:81]
	global_load_dwordx4 v[242:245], v246, s[80:81] offset:256
.Leinit511_skip:
	v_mul_f32_e32 v152, v119, v119
	v_fmac_f32_e32 v152, v118, v118
	v_fmac_f32_e32 v152, v120, v120
	v_cvt_pk_bf16_f32 v118, v118, v119
	v_cvt_pk_bf16_f32 v119, v120, v121
	v_mul_f32_e32 v120, v123, v123
	v_fmac_f32_e32 v120, v122, v122
	v_fmac_f32_e32 v120, v124, v124
	v_fmac_f32_e32 v152, v121, v121
	v_fmac_f32_e32 v120, v125, v125
	v_fmac_f32_e32 v152, v110, v110
	v_fmac_f32_e32 v120, v126, v126
	v_xor_b32_e32 v143, 16, v223
	v_fmac_f32_e32 v152, v111, v111
	v_fmac_f32_e32 v120, v127, v127
	v_cmp_lt_i32_e64 s[0:1], v143, v225
	v_fmac_f32_e32 v152, v112, v112
	v_fmac_f32_e32 v120, v128, v128
	v_cndmask_b32_e64 v143, v223, v143, s[0:1]
	v_fmac_f32_e32 v152, v113, v113
	v_fmac_f32_e32 v120, v129, v129
	v_lshlrev_b32_e32 v149, 2, v143
	v_add_f32_e32 v152, v152, v120
	ds_bpermute_b32 v153, v149, v152
	v_xor_b32_e32 v143, 32, v223
	v_cmp_lt_i32_e64 s[0:1], v143, v225
	v_lshl_add_u32 v142, s21, 8, v144
	v_cvt_pk_bf16_f32 v120, v110, v111
	v_cndmask_b32_e64 v143, v223, v143, s[0:1]
	v_lshlrev_b32_e32 v148, 2, v143
	s_waitcnt lgkmcnt(0)
	v_add_f32_e32 v110, v152, v153
	v_ashrrev_i32_e32 v143, 31, v142
	ds_bpermute_b32 v111, v148, v110
	v_lshl_or_b32 v140, s20, 8, v147
	v_lshlrev_b64 v[150:151], 11, v[142:143]
	v_ashrrev_i32_e32 v141, 31, v140
	v_lshl_add_u64 v[150:151], s[92:93], 0, v[150:151]
	s_lshl_b32 s0, s20, 2
	v_lshl_add_u64 v[150:151], v[140:141], 1, v[150:151]
	v_cvt_pk_bf16_f32 v121, v112, v113
	s_ashr_i32 s1, s0, 31
	global_store_dwordx4 v[150:151], v[118:121], off
	s_nop 1
	v_cvt_pk_bf16_f32 v118, v122, v123
	v_cvt_pk_bf16_f32 v119, v124, v125
	v_cvt_pk_bf16_f32 v120, v126, v127
	v_cvt_pk_bf16_f32 v121, v128, v129
	global_store_dwordx4 v[150:151], v[118:121], off offset:256
	s_and_saveexec_b64 s[28:29], s[36:37]
	s_cbranch_execz .LBB0_514
	s_waitcnt lgkmcnt(0)
	v_add_f32_e32 v110, v110, v111
	v_bfe_u32 v111, v110, 16, 1
	v_add3_u32 v112, v110, v111, s63
	v_lshlrev_b64 v[110:111], 5, v[142:143]
	v_lshl_add_u64 v[110:111], s[70:71], 0, v[110:111]
	v_lshl_add_u64 v[110:111], s[0:1], 1, v[110:111]
	s_lshl_b32 s76, s5, 1
	v_lshl_add_u64 v[110:111], v[110:111], 0, s[76:77]
	global_store_short_d16_hi v[110:111], v112, off

; DI float bflo(unsigned u) { return __uint_as_float(u << 16); }
; DI float bfhi(unsigned u) { return __uint_as_float(u & 0xffff0000u); }
;   DI void init(f32x4 (&acc)[2][2][4][2], const Unit& u, int wr, int wc, int fr, int fq) const {
;     ...
;       for (int m = 0; m < 4; ++m) { const bf16_t* rowp = src + (size_t)(row0 + ai * HALF + m * 16) * DM + col0;
; #pragma unroll
;         for (int bj = 0; bj < 2; ++bj) { const u32x4 w = *(const u32x4*)(rowp + bj * HALF);
;           acc[ai][bj][m][0] = (f32x4){bflo(w.x), bfhi(w.x), bflo(w.y), bfhi(w.y)} * ic; acc[ai][bj][m][1] = (f32x4){bflo(w.z), bfhi(w.z), bflo(w.w), bfhi(w.w)} * ic; } }
.LBB0_528:
	s_or_b64 exec, exec, s[28:29]
	s_mov_b64 s[0:1], -1
	s_and_b64 vcc, vcc, exec
	s_cbranch_vccz .LBB0_503
	s_waitcnt vmcnt(16)
	s_waitcnt lgkmcnt(0)
	v_lshlrev_b32_e32 v118, 16, v166
	v_and_b32_e32 v119, 0xffff0000, v166
	v_lshlrev_b32_e32 v120, 16, v167
	v_and_b32_e32 v121, 0xffff0000, v167
	v_lshlrev_b32_e32 v122, 16, v170
	v_and_b32_e32 v123, 0xffff0000, v170
	v_lshlrev_b32_e32 v124, 16, v171
	v_and_b32_e32 v125, 0xffff0000, v171
	v_lshlrev_b32_e32 v126, 16, v172
	v_and_b32_e32 v127, 0xffff0000, v172
	v_lshlrev_b32_e32 v128, 16, v173
	v_and_b32_e32 v129, 0xffff0000, v173
	v_lshlrev_b32_e32 v110, 16, v168
	v_and_b32_e32 v111, 0xffff0000, v168
	v_lshlrev_b32_e32 v112, 16, v169
	v_and_b32_e32 v113, 0xffff0000, v169
	v_lshlrev_b32_e32 v90, 16, v174
	v_and_b32_e32 v91, 0xffff0000, v174
	v_lshlrev_b32_e32 v92, 16, v175
	v_and_b32_e32 v93, 0xffff0000, v175
	v_lshlrev_b32_e32 v82, 16, v176
	v_and_b32_e32 v83, 0xffff0000, v176
	v_lshlrev_b32_e32 v84, 16, v177
	v_and_b32_e32 v85, 0xffff0000, v177
	v_lshlrev_b32_e32 v102, 16, v178
	v_and_b32_e32 v103, 0xffff0000, v178
	v_lshlrev_b32_e32 v104, 16, v179
	v_and_b32_e32 v105, 0xffff0000, v179
	v_lshlrev_b32_e32 v114, 16, v180
	v_and_b32_e32 v115, 0xffff0000, v180
	v_lshlrev_b32_e32 v116, 16, v181
	v_and_b32_e32 v117, 0xffff0000, v181
	v_lshlrev_b32_e32 v62, 16, v182
	v_and_b32_e32 v63, 0xffff0000, v182
	v_lshlrev_b32_e32 v64, 16, v183
	v_and_b32_e32 v65, 0xffff0000, v183
	v_lshlrev_b32_e32 v50, 16, v184
	v_and_b32_e32 v51, 0xffff0000, v184
	v_lshlrev_b32_e32 v52, 16, v185
	v_and_b32_e32 v53, 0xffff0000, v185
	v_lshlrev_b32_e32 v86, 16, v186
	v_and_b32_e32 v87, 0xffff0000, v186
	v_lshlrev_b32_e32 v88, 16, v187
	v_and_b32_e32 v89, 0xffff0000, v187
	v_lshlrev_b32_e32 v98, 16, v188
	v_and_b32_e32 v99, 0xffff0000, v188
	v_lshlrev_b32_e32 v100, 16, v189
	v_and_b32_e32 v101, 0xffff0000, v189
	v_lshlrev_b32_e32 v42, 16, v190
	v_and_b32_e32 v43, 0xffff0000, v190
	v_lshlrev_b32_e32 v44, 16, v191
	v_and_b32_e32 v45, 0xffff0000, v191
	v_lshlrev_b32_e32 v22, 16, v192
	v_and_b32_e32 v23, 0xffff0000, v192
	v_lshlrev_b32_e32 v24, 16, v193
	v_and_b32_e32 v25, 0xffff0000, v193
	v_lshlrev_b32_e32 v58, 16, v198
	v_and_b32_e32 v59, 0xffff0000, v198
	v_lshlrev_b32_e32 v60, 16, v199
	v_and_b32_e32 v61, 0xffff0000, v199
	v_lshlrev_b32_e32 v74, 16, v200
	v_and_b32_e32 v75, 0xffff0000, v200
	v_lshlrev_b32_e32 v76, 16, v201
	v_and_b32_e32 v77, 0xffff0000, v201
	v_lshlrev_b32_e32 v38, 16, v194
	v_and_b32_e32 v39, 0xffff0000, v194
	v_lshlrev_b32_e32 v40, 16, v195
	v_and_b32_e32 v41, 0xffff0000, v195
	v_lshlrev_b32_e32 v18, 16, v196
	v_and_b32_e32 v19, 0xffff0000, v196
	v_lshlrev_b32_e32 v20, 16, v197
	v_and_b32_e32 v21, 0xffff0000, v197
	v_lshlrev_b32_e32 v54, 16, v202
	v_and_b32_e32 v55, 0xffff0000, v202
	v_lshlrev_b32_e32 v56, 16, v203
	v_and_b32_e32 v57, 0xffff0000, v203
	v_lshlrev_b32_e32 v66, 16, v204
	v_and_b32_e32 v67, 0xffff0000, v204
	v_lshlrev_b32_e32 v68, 16, v205
	v_and_b32_e32 v69, 0xffff0000, v205
	v_lshlrev_b32_e32 v10, 16, v206
	v_and_b32_e32 v11, 0xffff0000, v206
	v_lshlrev_b32_e32 v12, 16, v207
	v_and_b32_e32 v13, 0xffff0000, v207
	v_lshlrev_b32_e32 v2, 16, v208
	v_and_b32_e32 v3, 0xffff0000, v208
	v_lshlrev_b32_e32 v4, 16, v209
	v_and_b32_e32 v5, 0xffff0000, v209
	v_lshlrev_b32_e32 v94, 16, v210
	v_and_b32_e32 v95, 0xffff0000, v210
	v_lshlrev_b32_e32 v96, 16, v211
	v_and_b32_e32 v97, 0xffff0000, v211
	v_lshlrev_b32_e32 v106, 16, v212
	v_and_b32_e32 v107, 0xffff0000, v212
	v_lshlrev_b32_e32 v108, 16, v213
	v_and_b32_e32 v109, 0xffff0000, v213
	v_lshlrev_b32_e32 v46, 16, v214
	v_and_b32_e32 v47, 0xffff0000, v214
	v_lshlrev_b32_e32 v48, 16, v215
	v_and_b32_e32 v49, 0xffff0000, v215
	v_lshlrev_b32_e32 v30, 16, v216
	v_and_b32_e32 v31, 0xffff0000, v216
	v_lshlrev_b32_e32 v32, 16, v217
	v_and_b32_e32 v33, 0xffff0000, v217
	v_lshlrev_b32_e32 v70, 16, v218
	v_and_b32_e32 v71, 0xffff0000, v218
	v_lshlrev_b32_e32 v72, 16, v219
	v_and_b32_e32 v73, 0xffff0000, v219
	v_lshlrev_b32_e32 v78, 16, v220
	v_and_b32_e32 v79, 0xffff0000, v220
	v_lshlrev_b32_e32 v80, 16, v221
	v_and_b32_e32 v81, 0xffff0000, v221
	v_lshlrev_b32_e32 v14, 16, v238
	v_and_b32_e32 v15, 0xffff0000, v238
	v_lshlrev_b32_e32 v16, 16, v239
	v_and_b32_e32 v17, 0xffff0000, v239
	v_lshlrev_b32_e32 v6, 16, v240
	v_and_b32_e32 v7, 0xffff0000, v240
	v_lshlrev_b32_e32 v8, 16, v241
	v_and_b32_e32 v9, 0xffff0000, v241
	v_lshlrev_b32_e32 v26, 16, v242
	v_and_b32_e32 v27, 0xffff0000, v242
	v_lshlrev_b32_e32 v28, 16, v243
	v_and_b32_e32 v29, 0xffff0000, v243
	v_lshlrev_b32_e32 v34, 16, v244
	v_and_b32_e32 v35, 0xffff0000, v244
	v_lshlrev_b32_e32 v36, 16, v245
	v_and_b32_e32 v37, 0xffff0000, v245
	s_mov_b32 s0, 0x0
	s_mov_b32 s1, 0x0
	s_branch .LBB0_503

; #define PG8_STAGE(bufoff, gbase, voff) do { _Pragma("unroll") for (int _i = 0; _i < 2; ++_i) \
;     __builtin_amdgcn_global_load_lds((const unsigned*)((const char*)(gbase) + (voff)[_i]), (PG8_LAS unsigned*)(lds + (bufoff) + ldsw + _i * 8192), 16, 0, 0); } while (0)
; #define PG8_LDA(dst, b, h) do { _Pragma("unroll") for (int m = 0; m < 4; ++m) _Pragma("unroll") for (int k = 0; k < 2; ++k) dst[m][k] = *(const PG8_LAS bf16x8*)(lds + PG8_SA(b, h) + aoff + m * 2048 + k * 1024); } while (0)
; #define PG8_LDB(dst, b, h) do { _Pragma("unroll") for (int n = 0; n < 2; ++n) _Pragma("unroll") for (int k = 0; k < 2; ++k) dst[n][k] = *(const PG8_LAS bf16x8*)(lds + PG8_SB(b, h) + boff + n * 2048 + k * 1024); } while (0)
; #define PG8_MMA(ai, bj, At, Bt) do { __builtin_amdgcn_s_setprio(1); _Pragma("unroll") for (int m = 0; m < 4; ++m) _Pragma("unroll") for (int n = 0; n < 2; ++n) _Pragma("unroll") for (int k = 0; k < 2; ++k) \
;     acc[ai][bj][m][n] = __builtin_amdgcn_mfma_f32_16x16x32_bf16(Bt[n][k], At[m][k], acc[ai][bj][m][n], 0, 0, 0); __builtin_amdgcn_s_setprio(0); } while (0)
; #define PG8_WAIT_V(n) asm volatile("s_waitcnt vmcnt(" #n ")" ::: "memory")
; #define PG8_WAIT_L(n) asm volatile("s_waitcnt lgkmcnt(" #n ")" ::: "memory")
; #define PG8_BAR __builtin_amdgcn_s_barrier()
; #define PG8_SCHED __builtin_amdgcn_sched_barrier(0)
; template <class Epi>
; DI void gemm_phase(const bf16_t* __restrict__ gA, const bf16_t* __restrict__ gBt, int M, int N, int K, const Epi& E, char* lds_generic) {
;     ...
;       PG8_LDB(B0, 0, 0); PG8_SCHED; PG8_LDA(At, 0, 0); PG8_STAGE(PG8_SA(1, 1), a1 + hstep, voffA);
;       PG8_WAIT_L(8); PG8_BAR; PG8_WAIT_L(0); PG8_MMA(0, 0, At, B0); PG8_BAR; PG8_SCHED;
;       PG8_LDB(B1, 0, 1); PG8_STAGE(PG8_SB(0, 0), b2, voffB);
;       PG8_BAR; PG8_WAIT_L(0); PG8_MMA(0, 1, At, B1); PG8_BAR;
;       PG8_LDA(At, 0, 1); PG8_STAGE(PG8_SA(0, 0), a2, voffA);
;       PG8_BAR; PG8_WAIT_L(0); PG8_MMA(1, 0, At, B0); PG8_BAR; PG8_SCHED;
;       PG8_STAGE(PG8_SB(0, 1), b2 + hstep, voffB);
;       PG8_WAIT_V(6); PG8_BAR; PG8_MMA(1, 1, At, B1); PG8_BAR;
.LBB0_684:
	ds_read_b128 v[140:143], v146
	ds_read_b128 v[148:151], v146 offset:1024
	ds_read_b128 v[152:155], v146 offset:2048
	ds_read_b128 v[156:159], v146 offset:3072
	s_add_u32 s28, s88, 0x100
	s_addc_u32 s29, s89, 0
	s_cmp_eq_u32 s23, 40
	s_cselect_b32 s91, s87, s29
	s_cselect_b32 s90, s86, s28
	s_cselect_b32 s31, s1, s22
	s_cselect_b32 s30, s0, s21
	s_add_i32 m0, s12, 0xc000
	ds_read_b128 v[166:169], v145
	ds_read_b128 v[170:173], v145 offset:1024
	ds_read_b128 v[174:177], v145 offset:2048
	ds_read_b128 v[178:181], v145 offset:3072
	ds_read_b128 v[182:185], v145 offset:4096
	ds_read_b128 v[186:189], v145 offset:5120
	ds_read_b128 v[190:193], v145 offset:6144
	ds_read_b128 v[194:197], v145 offset:7168
	global_load_lds_dwordx4 v136, s[88:89]
	s_add_i32 m0, s12, 0xe000
	s_nop 0
	global_load_lds_dwordx4 v138, s[88:89]
	s_barrier
	s_waitcnt lgkmcnt(0)
	s_waitcnt lgkmcnt(0)
	v_mfma_f32_16x16x32_bf16 v[126:129], v[140:143], v[166:169], v[126:129]
	v_mfma_f32_16x16x32_bf16 v[122:125], v[152:155], v[166:169], v[122:125]
	v_mfma_f32_16x16x32_bf16 v[110:113], v[140:143], v[174:177], v[110:113]
	v_mfma_f32_16x16x32_bf16 v[106:109], v[152:155], v[174:177], v[106:109]
	v_mfma_f32_16x16x32_bf16 v[94:97], v[140:143], v[182:185], v[94:97]
	v_mfma_f32_16x16x32_bf16 v[90:93], v[152:155], v[182:185], v[90:93]
	v_mfma_f32_16x16x32_bf16 v[78:81], v[140:143], v[190:193], v[78:81]
	v_mfma_f32_16x16x32_bf16 v[74:77], v[152:155], v[190:193], v[74:77]
	v_mfma_f32_16x16x32_bf16 v[126:129], v[148:151], v[170:173], v[126:129]
	v_mfma_f32_16x16x32_bf16 v[122:125], v[156:159], v[170:173], v[122:125]
	v_mfma_f32_16x16x32_bf16 v[110:113], v[148:151], v[178:181], v[110:113]
	v_mfma_f32_16x16x32_bf16 v[106:109], v[156:159], v[178:181], v[106:109]
	v_mfma_f32_16x16x32_bf16 v[94:97], v[148:151], v[186:189], v[94:97]
	v_mfma_f32_16x16x32_bf16 v[90:93], v[156:159], v[186:189], v[90:93]
	v_mfma_f32_16x16x32_bf16 v[78:81], v[148:151], v[194:197], v[78:81]
	v_mfma_f32_16x16x32_bf16 v[74:77], v[156:159], v[194:197], v[74:77]
	s_barrier
	ds_read_b128 v[198:201], v146 offset:16384
	ds_read_b128 v[202:205], v146 offset:17408
	s_mov_b32 m0, s13
	ds_read_b128 v[206:209], v146 offset:18432
	ds_read_b128 v[210:213], v146 offset:19456
	global_load_lds_dwordx4 v0, s[30:31]
	s_mov_b32 m0, s14
	s_nop 0
	global_load_lds_dwordx4 v134, s[30:31]
	s_barrier
	s_waitcnt lgkmcnt(0)
	s_waitcnt lgkmcnt(0)
	v_mfma_f32_16x16x32_bf16 v[118:121], v[198:201], v[166:169], v[118:121]
	v_mfma_f32_16x16x32_bf16 v[114:117], v[206:209], v[166:169], v[114:117]
	v_mfma_f32_16x16x32_bf16 v[102:105], v[198:201], v[174:177], v[102:105]
	v_mfma_f32_16x16x32_bf16 v[98:101], v[206:209], v[174:177], v[98:101]
	v_mfma_f32_16x16x32_bf16 v[86:89], v[198:201], v[182:185], v[86:89]
	v_mfma_f32_16x16x32_bf16 v[82:85], v[206:209], v[182:185], v[82:85]
	v_mfma_f32_16x16x32_bf16 v[70:73], v[198:201], v[190:193], v[70:73]
	v_mfma_f32_16x16x32_bf16 v[66:69], v[206:209], v[190:193], v[66:69]
	v_mfma_f32_16x16x32_bf16 v[118:121], v[202:205], v[170:173], v[118:121]
	v_mfma_f32_16x16x32_bf16 v[114:117], v[210:213], v[170:173], v[114:117]
	v_mfma_f32_16x16x32_bf16 v[102:105], v[202:205], v[178:181], v[102:105]
	v_mfma_f32_16x16x32_bf16 v[98:101], v[210:213], v[178:181], v[98:101]
	v_mfma_f32_16x16x32_bf16 v[86:89], v[202:205], v[186:189], v[86:89]
	v_mfma_f32_16x16x32_bf16 v[82:85], v[210:213], v[186:189], v[82:85]
	v_mfma_f32_16x16x32_bf16 v[70:73], v[202:205], v[194:197], v[70:73]
	v_mfma_f32_16x16x32_bf16 v[66:69], v[210:213], v[194:197], v[66:69]
	s_mov_b32 m0, s12
	s_barrier
	ds_read_b128 v[166:169], v145 offset:16384
	ds_read_b128 v[170:173], v145 offset:17408
	ds_read_b128 v[174:177], v145 offset:18432
	ds_read_b128 v[178:181], v145 offset:19456
	ds_read_b128 v[182:185], v145 offset:20480
	ds_read_b128 v[186:189], v145 offset:21504
	ds_read_b128 v[190:193], v145 offset:22528
	ds_read_b128 v[194:197], v145 offset:23552
	global_load_lds_dwordx4 v130, s[90:91]
	s_mov_b32 m0, s15
	s_nop 0
	global_load_lds_dwordx4 v132, s[90:91]
	s_barrier
	s_waitcnt lgkmcnt(0)
	s_waitcnt lgkmcnt(0)
	v_mfma_f32_16x16x32_bf16 v[62:65], v[140:143], v[166:169], v[62:65]
	v_mfma_f32_16x16x32_bf16 v[58:61], v[152:155], v[166:169], v[58:61]
	v_mfma_f32_16x16x32_bf16 v[46:49], v[140:143], v[174:177], v[46:49]
	v_mfma_f32_16x16x32_bf16 v[42:45], v[152:155], v[174:177], v[42:45]
	v_mfma_f32_16x16x32_bf16 v[30:33], v[140:143], v[182:185], v[30:33]
	v_mfma_f32_16x16x32_bf16 v[26:29], v[152:155], v[182:185], v[26:29]
	v_mfma_f32_16x16x32_bf16 v[14:17], v[140:143], v[190:193], v[14:17]
	v_mfma_f32_16x16x32_bf16 v[10:13], v[152:155], v[190:193], v[10:13]
	v_mfma_f32_16x16x32_bf16 v[62:65], v[148:151], v[170:173], v[62:65]
	v_mfma_f32_16x16x32_bf16 v[58:61], v[156:159], v[170:173], v[58:61]
	v_mfma_f32_16x16x32_bf16 v[46:49], v[148:151], v[178:181], v[46:49]
	v_mfma_f32_16x16x32_bf16 v[42:45], v[156:159], v[178:181], v[42:45]
	v_mfma_f32_16x16x32_bf16 v[30:33], v[148:151], v[186:189], v[30:33]
	v_mfma_f32_16x16x32_bf16 v[26:29], v[156:159], v[186:189], v[26:29]
	v_mfma_f32_16x16x32_bf16 v[14:17], v[148:151], v[194:197], v[14:17]
	v_mfma_f32_16x16x32_bf16 v[10:13], v[156:159], v[194:197], v[10:13]
	s_barrier
	s_add_u32 s24, s30, 0xb0000
	s_addc_u32 s25, s31, 0
	s_mov_b32 m0, s18
	s_nop 0
	global_load_lds_dwordx4 v0, s[24:25]
	s_mov_b32 m0, s35
	s_nop 0
	global_load_lds_dwordx4 v134, s[24:25]
	s_waitcnt vmcnt(6)
	s_barrier
; #define PG8_STAGE(bufoff, gbase, voff) do { _Pragma("unroll") for (int _i = 0; _i < 2; ++_i) \
;     __builtin_amdgcn_global_load_lds((const unsigned*)((const char*)(gbase) + (voff)[_i]), (PG8_LAS unsigned*)(lds + (bufoff) + ldsw + _i * 8192), 16, 0, 0); } while (0)
; #define PG8_LDA(dst, b, h) do { _Pragma("unroll") for (int m = 0; m < 4; ++m) _Pragma("unroll") for (int k = 0; k < 2; ++k) dst[m][k] = *(const PG8_LAS bf16x8*)(lds + PG8_SA(b, h) + aoff + m * 2048 + k * 1024); } while (0)
; #define PG8_LDB(dst, b, h) do { _Pragma("unroll") for (int n = 0; n < 2; ++n) _Pragma("unroll") for (int k = 0; k < 2; ++k) dst[n][k] = *(const PG8_LAS bf16x8*)(lds + PG8_SB(b, h) + boff + n * 2048 + k * 1024); } while (0)
; #define PG8_MMA(ai, bj, At, Bt) do { __builtin_amdgcn_s_setprio(1); _Pragma("unroll") for (int m = 0; m < 4; ++m) _Pragma("unroll") for (int n = 0; n < 2; ++n) _Pragma("unroll") for (int k = 0; k < 2; ++k) \
;     acc[ai][bj][m][n] = __builtin_amdgcn_mfma_f32_16x16x32_bf16(Bt[n][k], At[m][k], acc[ai][bj][m][n], 0, 0, 0); __builtin_amdgcn_s_setprio(0); } while (0)
; #define PG8_WAIT_V(n) asm volatile("s_waitcnt vmcnt(" #n ")" ::: "memory")
; #define PG8_WAIT_L(n) asm volatile("s_waitcnt lgkmcnt(" #n ")" ::: "memory")
; #define PG8_BAR __builtin_amdgcn_s_barrier()
; #define PG8_SCHED __builtin_amdgcn_sched_barrier(0)
; template <class Epi>
; DI void gemm_phase(const bf16_t* __restrict__ gA, const bf16_t* __restrict__ gBt, int M, int N, int K, const Epi& E, char* lds_generic) {
;     ...
;       PG8_LDB(B0, 1, 0); PG8_SCHED; PG8_LDA(At, 1, 0); PG8_STAGE(PG8_SA(0, 1), a2 + hstep, voffA);
;       PG8_WAIT_L(8); PG8_BAR; PG8_WAIT_L(0); PG8_MMA(0, 0, At, B0); PG8_BAR; PG8_SCHED;
;       PG8_LDB(B1, 1, 1); PG8_STAGE(PG8_SB(1, 0), b3, voffB);
;       PG8_BAR; PG8_WAIT_L(0); PG8_MMA(0, 1, At, B1); PG8_BAR;
;       PG8_LDA(At, 1, 1); PG8_STAGE(PG8_SA(1, 0), a3, voffA);
;       PG8_BAR; PG8_WAIT_L(0); PG8_MMA(1, 0, At, B0); PG8_BAR; PG8_SCHED;
;       PG8_STAGE(PG8_SB(1, 1), b3 + hstep, voffB);
;       PG8_WAIT_V(6); PG8_BAR; PG8_MMA(1, 1, At, B1); PG8_BAR;
	v_mfma_f32_16x16x32_bf16 v[54:57], v[198:201], v[166:169], v[54:57]
	v_mfma_f32_16x16x32_bf16 v[50:53], v[206:209], v[166:169], v[50:53]
	v_mfma_f32_16x16x32_bf16 v[38:41], v[198:201], v[174:177], v[38:41]
	v_mfma_f32_16x16x32_bf16 v[34:37], v[206:209], v[174:177], v[34:37]
	v_mfma_f32_16x16x32_bf16 v[22:25], v[198:201], v[182:185], v[22:25]
	v_mfma_f32_16x16x32_bf16 v[18:21], v[206:209], v[182:185], v[18:21]
	v_mfma_f32_16x16x32_bf16 v[6:9], v[198:201], v[190:193], v[6:9]
	v_mfma_f32_16x16x32_bf16 v[2:5], v[206:209], v[190:193], v[2:5]
	v_mfma_f32_16x16x32_bf16 v[54:57], v[202:205], v[170:173], v[54:57]
	v_mfma_f32_16x16x32_bf16 v[50:53], v[210:213], v[170:173], v[50:53]
	v_mfma_f32_16x16x32_bf16 v[38:41], v[202:205], v[178:181], v[38:41]
	v_mfma_f32_16x16x32_bf16 v[34:37], v[210:213], v[178:181], v[34:37]
	v_mfma_f32_16x16x32_bf16 v[22:25], v[202:205], v[186:189], v[22:25]
	v_mfma_f32_16x16x32_bf16 v[18:21], v[210:213], v[186:189], v[18:21]
	v_mfma_f32_16x16x32_bf16 v[6:9], v[202:205], v[194:197], v[6:9]
	v_mfma_f32_16x16x32_bf16 v[2:5], v[210:213], v[194:197], v[2:5]
	s_barrier
	ds_read_b128 v[140:143], v146 offset:32768
	ds_read_b128 v[148:151], v146 offset:33792
	ds_read_b128 v[152:155], v146 offset:34816
	ds_read_b128 v[156:159], v146 offset:35840
	s_add_u32 s24, s90, 0xb0000
	s_addc_u32 s25, s91, 0
	s_mov_b32 m0, s53
	ds_read_b128 v[166:169], v145 offset:32768
	ds_read_b128 v[170:173], v145 offset:33792
	ds_read_b128 v[174:177], v145 offset:34816
	ds_read_b128 v[178:181], v145 offset:35840
	ds_read_b128 v[182:185], v145 offset:36864
	ds_read_b128 v[186:189], v145 offset:37888
	ds_read_b128 v[190:193], v145 offset:38912
	ds_read_b128 v[194:197], v145 offset:39936
	global_load_lds_dwordx4 v130, s[24:25]
	s_mov_b32 m0, s58
	s_nop 0
	global_load_lds_dwordx4 v132, s[24:25]
	s_barrier
	s_waitcnt lgkmcnt(0)
	s_waitcnt lgkmcnt(0)
	v_mfma_f32_16x16x32_bf16 v[126:129], v[140:143], v[166:169], v[126:129]
	v_mfma_f32_16x16x32_bf16 v[122:125], v[152:155], v[166:169], v[122:125]
	v_mfma_f32_16x16x32_bf16 v[110:113], v[140:143], v[174:177], v[110:113]
	v_mfma_f32_16x16x32_bf16 v[106:109], v[152:155], v[174:177], v[106:109]
	v_mfma_f32_16x16x32_bf16 v[94:97], v[140:143], v[182:185], v[94:97]
	v_mfma_f32_16x16x32_bf16 v[90:93], v[152:155], v[182:185], v[90:93]
	v_mfma_f32_16x16x32_bf16 v[78:81], v[140:143], v[190:193], v[78:81]
	v_mfma_f32_16x16x32_bf16 v[74:77], v[152:155], v[190:193], v[74:77]
	v_mfma_f32_16x16x32_bf16 v[126:129], v[148:151], v[170:173], v[126:129]
	v_mfma_f32_16x16x32_bf16 v[122:125], v[156:159], v[170:173], v[122:125]
	v_mfma_f32_16x16x32_bf16 v[110:113], v[148:151], v[178:181], v[110:113]
	v_mfma_f32_16x16x32_bf16 v[106:109], v[156:159], v[178:181], v[106:109]
	v_mfma_f32_16x16x32_bf16 v[94:97], v[148:151], v[186:189], v[94:97]
	v_mfma_f32_16x16x32_bf16 v[90:93], v[156:159], v[186:189], v[90:93]
	v_mfma_f32_16x16x32_bf16 v[78:81], v[148:151], v[194:197], v[78:81]
	v_mfma_f32_16x16x32_bf16 v[74:77], v[156:159], v[194:197], v[74:77]
	s_barrier
	s_mov_b32 m0, s59
	ds_read_b128 v[198:201], v146 offset:49152
	ds_read_b128 v[202:205], v146 offset:50176
	ds_read_b128 v[206:209], v146 offset:51200
	ds_read_b128 v[210:213], v146 offset:52224
	s_add_u32 s24, s30, 0x80
	s_addc_u32 s25, s31, 0
	global_load_lds_dwordx4 v0, s[24:25]
	s_mov_b32 m0, s60
	s_nop 0
	s_add_u32 s24, s30, 0x80
	s_addc_u32 s25, s31, 0
	global_load_lds_dwordx4 v134, s[24:25]
	s_barrier
	s_waitcnt lgkmcnt(0)
	s_waitcnt lgkmcnt(0)
	v_mfma_f32_16x16x32_bf16 v[118:121], v[198:201], v[166:169], v[118:121]
	v_mfma_f32_16x16x32_bf16 v[114:117], v[206:209], v[166:169], v[114:117]
	v_mfma_f32_16x16x32_bf16 v[102:105], v[198:201], v[174:177], v[102:105]
	v_mfma_f32_16x16x32_bf16 v[98:101], v[206:209], v[174:177], v[98:101]
	v_mfma_f32_16x16x32_bf16 v[86:89], v[198:201], v[182:185], v[86:89]
	v_mfma_f32_16x16x32_bf16 v[82:85], v[206:209], v[182:185], v[82:85]
	v_mfma_f32_16x16x32_bf16 v[70:73], v[198:201], v[190:193], v[70:73]
	v_mfma_f32_16x16x32_bf16 v[66:69], v[206:209], v[190:193], v[66:69]
	v_mfma_f32_16x16x32_bf16 v[118:121], v[202:205], v[170:173], v[118:121]
	v_mfma_f32_16x16x32_bf16 v[114:117], v[210:213], v[170:173], v[114:117]
	v_mfma_f32_16x16x32_bf16 v[102:105], v[202:205], v[178:181], v[102:105]
	v_mfma_f32_16x16x32_bf16 v[98:101], v[210:213], v[178:181], v[98:101]
	v_mfma_f32_16x16x32_bf16 v[86:89], v[202:205], v[186:189], v[86:89]
	v_mfma_f32_16x16x32_bf16 v[82:85], v[210:213], v[186:189], v[82:85]
	v_mfma_f32_16x16x32_bf16 v[70:73], v[202:205], v[194:197], v[70:73]
	v_mfma_f32_16x16x32_bf16 v[66:69], v[210:213], v[194:197], v[66:69]
	s_mov_b32 m0, s62
	s_barrier
	ds_read_b128 v[166:169], v145 offset:49152
	ds_read_b128 v[170:173], v145 offset:50176
	ds_read_b128 v[174:177], v145 offset:51200
	ds_read_b128 v[178:181], v145 offset:52224
	ds_read_b128 v[182:185], v145 offset:53248
	ds_read_b128 v[186:189], v145 offset:54272
	ds_read_b128 v[190:193], v145 offset:55296
	ds_read_b128 v[194:197], v145 offset:56320
	s_add_u32 s24, s90, 0x80
	s_addc_u32 s25, s91, 0
	global_load_lds_dwordx4 v130, s[24:25]
	s_mov_b32 m0, s72
	s_nop 0
	s_add_u32 s24, s90, 0x80
	s_addc_u32 s25, s91, 0
	global_load_lds_dwordx4 v132, s[24:25]
	s_barrier
; DI bf16_t f2bf(float x) { unsigned u = __float_as_uint(x); u += 0x7fffu + ((u >> 16) & 1u); return (bf16_t)(u >> 16); }
; DI float bflo(unsigned u) { return __uint_as_float(u << 16); }
; DI float bfhi(unsigned u) { return __uint_as_float(u & 0xffff0000u); }
; DI unsigned pack2(float lo, float hi) { f32x2_t v = {lo, hi}; return __builtin_bit_cast(unsigned, __builtin_convertvector(v, bf16x2_t)); }
; #define PG8_LAS __attribute__((address_space(3)))
;   DI void init(f32x4 (&acc)[2][2][4][2], const Unit& u, int wr, int wc, int fr, int fq) const {
;     ...
;       for (int m = 0; m < 4; ++m) { const bf16_t* rowp = src + (size_t)(row0 + ai * HALF + m * 16) * DM + col0;
; #pragma unroll
;         for (int bj = 0; bj < 2; ++bj) { const u32x4 w = *(const u32x4*)(rowp + bj * HALF);
;           acc[ai][bj][m][0] = (f32x4){bflo(w.x), bfhi(w.x), bflo(w.y), bfhi(w.y)} * ic; acc[ai][bj][m][1] = (f32x4){bflo(w.z), bfhi(w.z), bflo(w.w), bfhi(w.w)} * ic; } }
;   }
;   DI void operator()(const f32x4 (&acc)[2][2][4][2], const Unit& u, int wr, int wc, int fr, int fq, const PG8_LAS float*) const {
;     const int row0 = u.pm * BM + wr * 64 + fr, col0 = u.pn * BM + wc * 32 + 8 * fq;
; #pragma unroll
;     for (int ai = 0; ai < 2; ++ai)
; #pragma unroll
;       for (int m = 0; m < 4; ++m) { const int row = row0 + ai * HALF + m * 16; bf16_t* rowp = dst + (size_t)row * DM + col0; float ss = 0.f;
; #pragma unroll
;         for (int bj = 0; bj < 2; ++bj) { const f32x4 v0 = acc[ai][bj][m][0] * coef, v1 = acc[ai][bj][m][1] * coef;
;           ss += v0[0] * v0[0] + v0[1] * v0[1] + v0[2] * v0[2] + v0[3] * v0[3] + v1[0] * v1[0] + v1[1] * v1[1] + v1[2] * v1[2] + v1[3] * v1[3];
;           u32x4 w; w.x = pack2(v0[0], v0[1]); w.y = pack2(v0[2], v0[3]); w.z = pack2(v1[0], v1[1]); w.w = pack2(v1[2], v1[3]);
;           *(u32x4*)(rowp + bj * HALF) = w; }
;         ss += __shfl_xor(ss, 16); ss += __shfl_xor(ss, 32);
;         if (fq == 0) ssq[(size_t)row * 16 + u.pn * 4 + wc] = f2bf(ss); }
	s_waitcnt lgkmcnt(0)
	s_waitcnt lgkmcnt(0)
	v_mfma_f32_16x16x32_bf16 v[62:65], v[140:143], v[166:169], v[62:65]
	v_mfma_f32_16x16x32_bf16 v[58:61], v[152:155], v[166:169], v[58:61]
	v_mfma_f32_16x16x32_bf16 v[46:49], v[140:143], v[174:177], v[46:49]
	v_mfma_f32_16x16x32_bf16 v[42:45], v[152:155], v[174:177], v[42:45]
	v_mfma_f32_16x16x32_bf16 v[30:33], v[140:143], v[182:185], v[30:33]
	v_mfma_f32_16x16x32_bf16 v[26:29], v[152:155], v[182:185], v[26:29]
	v_mfma_f32_16x16x32_bf16 v[14:17], v[140:143], v[190:193], v[14:17]
	v_mfma_f32_16x16x32_bf16 v[10:13], v[152:155], v[190:193], v[10:13]
	v_mfma_f32_16x16x32_bf16 v[62:65], v[148:151], v[170:173], v[62:65]
	v_mfma_f32_16x16x32_bf16 v[58:61], v[156:159], v[170:173], v[58:61]
	v_mfma_f32_16x16x32_bf16 v[46:49], v[148:151], v[178:181], v[46:49]
	v_mfma_f32_16x16x32_bf16 v[42:45], v[156:159], v[178:181], v[42:45]
	v_mfma_f32_16x16x32_bf16 v[30:33], v[148:151], v[186:189], v[30:33]
	v_mfma_f32_16x16x32_bf16 v[26:29], v[156:159], v[186:189], v[26:29]
	v_mfma_f32_16x16x32_bf16 v[14:17], v[148:151], v[194:197], v[14:17]
	v_mfma_f32_16x16x32_bf16 v[10:13], v[156:159], v[194:197], v[10:13]
	s_barrier
	s_add_u32 s24, s30, 0xb0080
	s_addc_u32 s25, s31, 0
	s_mov_b32 m0, s74
	s_nop 0
	global_load_lds_dwordx4 v0, s[24:25]
	s_mov_b32 m0, s19
	s_nop 0
	global_load_lds_dwordx4 v134, s[24:25]
	s_waitcnt vmcnt(6)
	s_barrier
	v_mfma_f32_16x16x32_bf16 v[54:57], v[198:201], v[166:169], v[54:57]
	v_mfma_f32_16x16x32_bf16 v[50:53], v[206:209], v[166:169], v[50:53]
	v_mfma_f32_16x16x32_bf16 v[38:41], v[198:201], v[174:177], v[38:41]
	v_mfma_f32_16x16x32_bf16 v[34:37], v[206:209], v[174:177], v[34:37]
	v_mfma_f32_16x16x32_bf16 v[22:25], v[198:201], v[182:185], v[22:25]
	v_mfma_f32_16x16x32_bf16 v[18:21], v[206:209], v[182:185], v[18:21]
	v_mfma_f32_16x16x32_bf16 v[6:9], v[198:201], v[190:193], v[6:9]
	v_mfma_f32_16x16x32_bf16 v[2:5], v[206:209], v[190:193], v[2:5]
	v_mfma_f32_16x16x32_bf16 v[54:57], v[202:205], v[170:173], v[54:57]
	v_mfma_f32_16x16x32_bf16 v[50:53], v[210:213], v[170:173], v[50:53]
	v_mfma_f32_16x16x32_bf16 v[38:41], v[202:205], v[178:181], v[38:41]
	v_mfma_f32_16x16x32_bf16 v[34:37], v[210:213], v[178:181], v[34:37]
	v_mfma_f32_16x16x32_bf16 v[22:25], v[202:205], v[186:189], v[22:25]
	v_mfma_f32_16x16x32_bf16 v[18:21], v[210:213], v[186:189], v[18:21]
	v_mfma_f32_16x16x32_bf16 v[6:9], v[202:205], v[194:197], v[6:9]
	v_mfma_f32_16x16x32_bf16 v[2:5], v[210:213], v[194:197], v[2:5]
	s_add_i32 s23, s23, 2
	s_add_u32 s21, s21, 0x100
	s_addc_u32 s22, s22, 0
	s_cmp_gt_u32 s23, 41
	s_mov_b64 s[88:89], s[28:29]
	s_barrier
	s_cbranch_scc0 .LBB0_684
	s_cmp_eq_u64 s[38:39], 0
	s_cbranch_scc1 .Leinit684_skip
	v_lshl_add_u32 v246, s20, 8, v144
	v_lshl_or_b32 v247, s8, 8, v147
	v_lshlrev_b32_e32 v246, 11, v246
	v_lshl_add_u32 v246, v247, 1, v246
	global_load_dwordx4 v[166:169], v246, s[82:83]
	global_load_dwordx4 v[170:173], v246, s[82:83] offset:256
	s_add_u32 s24, s82, 0x8000
	s_addc_u32 s25, s83, 0
	global_load_dwordx4 v[174:177], v246, s[24:25]
	global_load_dwordx4 v[178:181], v246, s[24:25] offset:256
	s_add_u32 s24, s82, 0x10000
	s_addc_u32 s25, s83, 0
	global_load_dwordx4 v[182:185], v246, s[24:25]
	global_load_dwordx4 v[186:189], v246, s[24:25] offset:256
	s_add_u32 s24, s82, 0x18000
	s_addc_u32 s25, s83, 0
	global_load_dwordx4 v[190:193], v246, s[24:25]
	global_load_dwordx4 v[198:201], v246, s[24:25] offset:256
	s_add_u32 s24, s82, 0x40000
	s_addc_u32 s25, s83, 0
	global_load_dwordx4 v[194:197], v246, s[24:25]
	global_load_dwordx4 v[202:205], v246, s[24:25] offset:256
	s_add_u32 s24, s82, 0x48000
	s_addc_u32 s25, s83, 0
	global_load_dwordx4 v[206:209], v246, s[24:25]
	global_load_dwordx4 v[210:213], v246, s[24:25] offset:256
	s_add_u32 s24, s82, 0x50000
	s_addc_u32 s25, s83, 0
	global_load_dwordx4 v[214:217], v246, s[24:25]
	global_load_dwordx4 v[218:221], v246, s[24:25] offset:256
	s_add_u32 s24, s82, 0x58000
	s_addc_u32 s25, s83, 0
	global_load_dwordx4 v[238:241], v246, s[24:25]
	global_load_dwordx4 v[242:245], v246, s[24:25] offset:256
.Leinit684_skip:
	v_pk_mul_f32 v[126:127], v[126:127], 0.5 op_sel_hi:[1,0]
	v_pk_mul_f32 v[128:129], v[128:129], 0.5 op_sel_hi:[1,0]
	v_mul_f32_e32 v154, v127, v127
	v_fmac_f32_e32 v154, v126, v126
	v_fmac_f32_e32 v154, v128, v128
	v_pk_mul_f32 v[118:119], v[118:119], 0.5 op_sel_hi:[1,0]
	v_pk_mul_f32 v[152:153], v[124:125], 0.5 op_sel_hi:[1,0]
	v_pk_mul_f32 v[124:125], v[122:123], 0.5 op_sel_hi:[1,0]
	v_fmac_f32_e32 v154, v129, v129
	v_cvt_pk_bf16_f32 v123, v128, v129
	v_pk_mul_f32 v[128:129], v[114:115], 0.5 op_sel_hi:[1,0]
	v_mul_f32_e32 v114, v119, v119
	v_pk_mul_f32 v[120:121], v[120:121], 0.5 op_sel_hi:[1,0]
	v_fmac_f32_e32 v114, v118, v118
	v_fmac_f32_e32 v114, v120, v120
	v_fmac_f32_e32 v114, v121, v121
	v_fmac_f32_e32 v154, v124, v124
	v_fmac_f32_e32 v114, v128, v128
	v_xor_b32_e32 v143, 16, v223
	v_fmac_f32_e32 v154, v125, v125
	v_cvt_pk_bf16_f32 v122, v126, v127
	v_pk_mul_f32 v[126:127], v[116:117], 0.5 op_sel_hi:[1,0]
	v_fmac_f32_e32 v114, v129, v129
	v_cmp_lt_i32_e32 vcc, v143, v225
	v_fmac_f32_e32 v154, v152, v152
	v_fmac_f32_e32 v114, v126, v126
	v_cndmask_b32_e32 v143, v223, v143, vcc
	v_fmac_f32_e32 v154, v153, v153
	v_fmac_f32_e32 v114, v127, v127
	v_lshlrev_b32_e32 v149, 2, v143
	v_add_f32_e32 v114, v154, v114
	ds_bpermute_b32 v115, v149, v114
	v_xor_b32_e32 v143, 32, v223
	v_cmp_lt_i32_e32 vcc, v143, v225
	v_lshl_add_u32 v142, s9, 8, v144
	v_lshl_or_b32 v140, s76, 8, v147
	v_cndmask_b32_e32 v143, v223, v143, vcc
	v_lshlrev_b32_e32 v148, 2, v143
	s_waitcnt lgkmcnt(0)
	v_add_f32_e32 v114, v114, v115
	ds_bpermute_b32 v115, v148, v114
	v_ashrrev_i32_e32 v143, 31, v142
	v_lshlrev_b64 v[150:151], 11, v[142:143]
	v_ashrrev_i32_e32 v141, 31, v140
	s_lshl_b32 s28, s76, 2
	v_lshl_add_u64 v[150:151], s[26:27], 0, v[150:151]
	s_ashr_i32 s29, s28, 31
	v_lshl_add_u64 v[150:151], v[140:141], 1, v[150:151]
	v_cvt_pk_bf16_f32 v124, v124, v125
	v_cvt_pk_bf16_f32 v125, v152, v153
	v_cvt_pk_bf16_f32 v116, v118, v119
	v_cvt_pk_bf16_f32 v117, v120, v121
	v_cvt_pk_bf16_f32 v118, v128, v129
	v_cvt_pk_bf16_f32 v119, v126, v127
	global_store_dwordx4 v[150:151], v[122:125], off
	global_store_dwordx4 v[150:151], v[116:119], off offset:256
	s_and_saveexec_b64 s[30:31], s[36:37]
	s_cbranch_execz .LBB0_687
	s_waitcnt lgkmcnt(0)
	v_add_f32_e32 v114, v114, v115
	v_bfe_u32 v115, v114, 16, 1
	v_add3_u32 v116, v114, v115, s63
	v_lshlrev_b64 v[114:115], 5, v[142:143]
	v_lshl_add_u64 v[114:115], s[84:85], 0, v[114:115]
	v_lshl_add_u64 v[114:115], s[28:29], 1, v[114:115]
	s_lshl_b32 s76, s7, 1
	v_lshl_add_u64 v[114:115], v[114:115], 0, s[76:77]
	global_store_short_d16_hi v[114:115], v116, off

; DI float bflo(unsigned u) { return __uint_as_float(u << 16); }
; DI float bfhi(unsigned u) { return __uint_as_float(u & 0xffff0000u); }
;   DI void init(f32x4 (&acc)[2][2][4][2], const Unit& u, int wr, int wc, int fr, int fq) const {
;     ...
;       for (int m = 0; m < 4; ++m) { const bf16_t* rowp = src + (size_t)(row0 + ai * HALF + m * 16) * DM + col0;
; #pragma unroll
;         for (int bj = 0; bj < 2; ++bj) { const u32x4 w = *(const u32x4*)(rowp + bj * HALF);
;           acc[ai][bj][m][0] = (f32x4){bflo(w.x), bfhi(w.x), bflo(w.y), bfhi(w.y)} * ic; acc[ai][bj][m][1] = (f32x4){bflo(w.z), bfhi(w.z), bflo(w.w), bfhi(w.w)} * ic; } }
.LBB0_701:
	s_or_b64 exec, exec, s[30:31]
	s_mov_b64 s[28:29], -1
	s_and_b64 vcc, exec, s[38:39]
	s_cbranch_vccz .LBB0_672
	s_waitcnt vmcnt(16)
	s_waitcnt lgkmcnt(0)
	v_lshlrev_b32_e32 v126, 16, v166
	v_and_b32_e32 v127, 0xffff0000, v166
	v_lshlrev_b32_e32 v128, 16, v167
	v_and_b32_e32 v129, 0xffff0000, v167
	v_lshlrev_b32_e32 v118, 16, v170
	v_and_b32_e32 v119, 0xffff0000, v170
	v_lshlrev_b32_e32 v120, 16, v171
	v_and_b32_e32 v121, 0xffff0000, v171
	v_lshlrev_b32_e32 v122, 16, v168
	v_and_b32_e32 v123, 0xffff0000, v168
	v_lshlrev_b32_e32 v124, 16, v169
	v_and_b32_e32 v125, 0xffff0000, v169
	v_lshlrev_b32_e32 v114, 16, v172
	v_and_b32_e32 v115, 0xffff0000, v172
	v_lshlrev_b32_e32 v116, 16, v173
	v_and_b32_e32 v117, 0xffff0000, v173
	v_lshlrev_b32_e32 v110, 16, v174
	v_and_b32_e32 v111, 0xffff0000, v174
	v_lshlrev_b32_e32 v112, 16, v175
	v_and_b32_e32 v113, 0xffff0000, v175
	v_lshlrev_b32_e32 v106, 16, v176
	v_and_b32_e32 v107, 0xffff0000, v176
	v_lshlrev_b32_e32 v108, 16, v177
	v_and_b32_e32 v109, 0xffff0000, v177
	v_lshlrev_b32_e32 v102, 16, v178
	v_and_b32_e32 v103, 0xffff0000, v178
	v_lshlrev_b32_e32 v104, 16, v179
	v_and_b32_e32 v105, 0xffff0000, v179
	v_lshlrev_b32_e32 v98, 16, v180
	v_and_b32_e32 v99, 0xffff0000, v180
	v_lshlrev_b32_e32 v100, 16, v181
	v_and_b32_e32 v101, 0xffff0000, v181
	v_lshlrev_b32_e32 v94, 16, v182
	v_and_b32_e32 v95, 0xffff0000, v182
	v_lshlrev_b32_e32 v96, 16, v183
	v_and_b32_e32 v97, 0xffff0000, v183
	v_lshlrev_b32_e32 v90, 16, v184
	v_and_b32_e32 v91, 0xffff0000, v184
	v_lshlrev_b32_e32 v92, 16, v185
	v_and_b32_e32 v93, 0xffff0000, v185
	v_lshlrev_b32_e32 v86, 16, v186
	v_and_b32_e32 v87, 0xffff0000, v186
	v_lshlrev_b32_e32 v88, 16, v187
	v_and_b32_e32 v89, 0xffff0000, v187
	v_lshlrev_b32_e32 v82, 16, v188
	v_and_b32_e32 v83, 0xffff0000, v188
	v_lshlrev_b32_e32 v84, 16, v189
	v_and_b32_e32 v85, 0xffff0000, v189
	v_lshlrev_b32_e32 v78, 16, v190
	v_and_b32_e32 v79, 0xffff0000, v190
	v_lshlrev_b32_e32 v80, 16, v191
	v_and_b32_e32 v81, 0xffff0000, v191
	v_lshlrev_b32_e32 v74, 16, v192
	v_and_b32_e32 v75, 0xffff0000, v192
	v_lshlrev_b32_e32 v76, 16, v193
	v_and_b32_e32 v77, 0xffff0000, v193
	v_lshlrev_b32_e32 v54, 16, v202
	v_lshlrev_b32_e32 v62, 16, v194
	v_and_b32_e32 v63, 0xffff0000, v194
	v_lshlrev_b32_e32 v70, 16, v198
	v_and_b32_e32 v71, 0xffff0000, v198
	v_lshlrev_b32_e32 v72, 16, v199
	v_and_b32_e32 v73, 0xffff0000, v199
	v_lshlrev_b32_e32 v66, 16, v200
	v_and_b32_e32 v67, 0xffff0000, v200
	v_lshlrev_b32_e32 v68, 16, v201
	v_and_b32_e32 v69, 0xffff0000, v201
	v_lshlrev_b32_e32 v64, 16, v195
	v_and_b32_e32 v65, 0xffff0000, v195
	v_lshlrev_b32_e32 v58, 16, v196
	v_and_b32_e32 v59, 0xffff0000, v196
	v_lshlrev_b32_e32 v60, 16, v197
	v_and_b32_e32 v61, 0xffff0000, v197
	v_and_b32_e32 v55, 0xffff0000, v202
	v_lshlrev_b32_e32 v56, 16, v203
	v_and_b32_e32 v57, 0xffff0000, v203
	v_lshlrev_b32_e32 v50, 16, v204
	v_and_b32_e32 v51, 0xffff0000, v204
	v_lshlrev_b32_e32 v52, 16, v205
	v_and_b32_e32 v53, 0xffff0000, v205
	v_lshlrev_b32_e32 v46, 16, v206
	v_and_b32_e32 v47, 0xffff0000, v206
	v_lshlrev_b32_e32 v48, 16, v207
	v_and_b32_e32 v49, 0xffff0000, v207
	v_lshlrev_b32_e32 v42, 16, v208
	v_and_b32_e32 v43, 0xffff0000, v208
	v_lshlrev_b32_e32 v44, 16, v209
	v_and_b32_e32 v45, 0xffff0000, v209
	v_lshlrev_b32_e32 v38, 16, v210
	v_and_b32_e32 v39, 0xffff0000, v210
	v_lshlrev_b32_e32 v40, 16, v211
	v_and_b32_e32 v41, 0xffff0000, v211
	v_lshlrev_b32_e32 v34, 16, v212
	v_and_b32_e32 v35, 0xffff0000, v212
	v_lshlrev_b32_e32 v36, 16, v213
	v_and_b32_e32 v37, 0xffff0000, v213
	v_lshlrev_b32_e32 v30, 16, v214
	v_and_b32_e32 v31, 0xffff0000, v214
	v_lshlrev_b32_e32 v32, 16, v215
	v_and_b32_e32 v33, 0xffff0000, v215
	v_lshlrev_b32_e32 v26, 16, v216
	v_and_b32_e32 v27, 0xffff0000, v216
	v_lshlrev_b32_e32 v28, 16, v217
	v_and_b32_e32 v29, 0xffff0000, v217
	v_lshlrev_b32_e32 v22, 16, v218
	v_and_b32_e32 v23, 0xffff0000, v218
	v_lshlrev_b32_e32 v24, 16, v219
	v_and_b32_e32 v25, 0xffff0000, v219
	v_lshlrev_b32_e32 v18, 16, v220
	v_and_b32_e32 v19, 0xffff0000, v220
	v_lshlrev_b32_e32 v20, 16, v221
	v_and_b32_e32 v21, 0xffff0000, v221
	v_lshlrev_b32_e32 v14, 16, v238
	v_and_b32_e32 v15, 0xffff0000, v238
	v_lshlrev_b32_e32 v16, 16, v239
	v_and_b32_e32 v17, 0xffff0000, v239
	v_lshlrev_b32_e32 v10, 16, v240
	v_and_b32_e32 v11, 0xffff0000, v240
	v_lshlrev_b32_e32 v12, 16, v241
	v_and_b32_e32 v13, 0xffff0000, v241
	v_lshlrev_b32_e32 v6, 16, v242
	v_and_b32_e32 v7, 0xffff0000, v242
	v_lshlrev_b32_e32 v8, 16, v243
	v_and_b32_e32 v9, 0xffff0000, v243
	v_lshlrev_b32_e32 v2, 16, v244
	v_and_b32_e32 v3, 0xffff0000, v244
	v_lshlrev_b32_e32 v4, 16, v245
	v_and_b32_e32 v5, 0xffff0000, v245
	s_mov_b32 s9, 0x58000
	s_mov_b32 s22, 0x58000
	s_mov_b32 s23, 0x0
	s_mov_b32 s28, 0x0
	s_mov_b32 s29, 0x0
	s_branch .LBB0_672
